# v19 plus the 14 remaining final reduction steps in pass A fused into v_add_f32_dpp row_bcast:31 (zero-init + dpp mov + add -> one op)
# speedup vs baseline: 1.0060x; 1.0005x over previous
.LBB0_680:
	v_lshlrev_b32_e32 v0, 16, v75
	v_lshlrev_b32_e32 v96, 16, v37
	v_lshlrev_b32_e32 v94, 16, v39
	v_sub_f32_e32 v0, v0, v96
	v_sub_f32_e32 v1, v96, v94
	v_lshlrev_b32_e32 v92, 16, v46
	v_lshlrev_b32_e32 v2, 16, v48
	s_waitcnt vmcnt(9)
	v_fmac_f32_e32 v96, v84, v0
	v_sub_f32_e32 v0, v94, v92
	v_fmac_f32_e32 v94, v1, v84
	v_sub_f32_e32 v1, v92, v2
	v_lshlrev_b32_e32 v4, 16, v27
	v_lshlrev_b32_e32 v5, 16, v43
	v_fmac_f32_e32 v92, v0, v84
	v_fma_f32 v90, v1, v84, v2
	v_lshlrev_b32_e32 v1, 16, v38
	v_lshlrev_b32_e32 v0, 16, v76
	v_lshlrev_b32_e32 v7, 16, v50
	v_mov_b32_e32 v6, v1
	v_pk_add_f32 v[0:1], v[0:1], v[4:5] neg_lo:[0,1] neg_hi:[0,1]
	v_lshlrev_b32_e32 v11, 16, v42
	s_waitcnt vmcnt(8)
	v_pk_fma_f32 v[8:9], v[22:23], v[0:1], v[4:5] op_sel_hi:[0,1,1]
	v_lshlrev_b32_e32 v10, 16, v25
	v_pk_add_f32 v[4:5], v[4:5], v[6:7] neg_lo:[0,1] neg_hi:[0,1]
	v_lshlrev_b32_e32 v95, 16, v55
	v_lshlrev_b32_e32 v93, 16, v62
	v_pk_add_f32 v[0:1], v[10:11], -1.0 op_sel_hi:[1,0]
	v_pk_fma_f32 v[14:15], v[4:5], v[22:23], v[6:7] op_sel_hi:[1,0,1]
	v_sub_f32_e32 v2, v2, v95
	v_sub_f32_e32 v6, v95, v93
	v_lshlrev_b32_e32 v91, 16, v64
	v_lshlrev_b32_e32 v89, 16, v72
	s_waitcnt vmcnt(6)
	v_mul_f32_e32 v97, v85, v8
	s_waitcnt vmcnt(5)
	v_pk_fma_f32 v[0:1], v[0:1], v[26:27], 1.0 op_sel_hi:[1,0,0]
	v_lshlrev_b32_e32 v18, 16, v59
	v_fmac_f32_e32 v95, v2, v84
	v_sub_f32_e32 v2, v93, v91
	v_fmac_f32_e32 v93, v6, v84
	v_lshlrev_b32_e32 v19, 16, v70
	v_sub_f32_e32 v6, v91, v89
	v_lshlrev_b32_e32 v12, 16, v40
	v_lshlrev_b32_e32 v13, 16, v49
	v_mul_f32_e32 v29, v97, v97
	v_pk_mul_f32 v[0:1], v[8:9], v[0:1]
	v_mul_f32_e32 v98, v85, v14
	v_mul_f32_e32 v99, v85, v9
	v_lshlrev_b32_e32 v8, 16, v53
	v_lshlrev_b32_e32 v9, 16, v65
	v_fmac_f32_e32 v89, v6, v84
	v_pk_mov_b32 v[6:7], v[6:7], v[18:19] op_sel:[1,0]
	v_mul_f32_e32 v34, v98, v98
	v_pk_add_f32 v[4:5], v[12:13], -1.0 op_sel_hi:[1,0]
	v_pk_add_f32 v[6:7], v[6:7], v[8:9] neg_lo:[0,1] neg_hi:[0,1]
	v_add_f32_dpp v119, v29, v29 quad_perm:[1,0,3,2] row_mask:0xf bank_mask:0xf
	v_pk_fma_f32 v[4:5], v[4:5], v[26:27], 1.0 op_sel_hi:[1,0,0]
	v_mul_f32_e32 v102, v99, v99
	v_mul_f32_e32 v100, v85, v15
	v_pk_fma_f32 v[30:31], v[6:7], v[22:23], v[8:9] op_sel_hi:[1,0,1]
	v_pk_add_f32 v[8:9], v[8:9], v[18:19] neg_lo:[0,1] neg_hi:[0,1]
	v_add_f32_dpp v29, v34, v34 quad_perm:[1,0,3,2] row_mask:0xf bank_mask:0xf
	v_pk_mul_f32 v[4:5], v[14:15], v[4:5]
	v_mul_f32_e32 v106, v100, v100
	v_mul_f32_e32 v104, v85, v30
	v_lshlrev_b32_e32 v15, 16, v67
	v_lshlrev_b32_e32 v14, 16, v58
	v_pk_fma_f32 v[18:19], v[8:9], v[22:23], v[18:19] op_sel_hi:[1,0,1]
	v_add_f32_dpp v34, v102, v102 quad_perm:[1,0,3,2] row_mask:0xf bank_mask:0xf
	v_lshlrev_b32_e32 v16, 16, v60
	v_lshlrev_b32_e32 v17, 16, v73
	v_fmac_f32_e32 v91, v2, v84
	v_mul_f32_e32 v2, v104, v104
	v_pk_add_f32 v[6:7], v[14:15], -1.0 op_sel_hi:[1,0]
	v_mul_f32_e32 v110, v85, v18
	v_add_f32_dpp v102, v106, v106 quad_perm:[1,0,3,2] row_mask:0xf bank_mask:0xf
	v_pk_fma_f32 v[6:7], v[6:7], v[26:27], 1.0 op_sel_hi:[1,0,0]
	v_mul_f32_e32 v113, v110, v110
	v_pk_add_f32 v[8:9], v[16:17], -1.0 op_sel_hi:[1,0]
	v_mul_f32_e32 v111, v85, v31
	v_add_f32_dpp v106, v2, v2 quad_perm:[1,0,3,2] row_mask:0xf bank_mask:0xf
	v_pk_mul_f32 v[6:7], v[30:31], v[6:7]
	v_pk_fma_f32 v[8:9], v[8:9], v[26:27], 1.0 op_sel_hi:[1,0,0]
	v_mul_f32_e32 v31, v111, v111
	v_mul_f32_e32 v112, v85, v19
	v_add_f32_dpp v2, v113, v113 quad_perm:[1,0,3,2] row_mask:0xf bank_mask:0xf
	v_mul_f32_e32 v32, v96, v0
	v_pk_mul_f32 v[8:9], v[18:19], v[8:9]
	v_mul_f32_e32 v19, v112, v112
	v_add_f32_dpp v113, v31, v31 quad_perm:[1,0,3,2] row_mask:0xf bank_mask:0xf
	s_waitcnt vmcnt(4)
	v_mul_f32_e32 v33, v86, v32
	v_mul_f32_e32 v35, v94, v4
	v_add_f32_dpp v31, v19, v19 quad_perm:[1,0,3,2] row_mask:0xf bank_mask:0xf
	v_mul_f32_e32 v101, v86, v35
	v_mul_f32_e32 v30, v95, v6
	v_add_f32_dpp v19, v33, v33 quad_perm:[1,0,3,2] row_mask:0xf bank_mask:0xf
	v_mul_f32_e32 v109, v86, v30
	v_mul_f32_e32 v18, v93, v8
	v_add_f32_dpp v32, v101, v101 quad_perm:[1,0,3,2] row_mask:0xf bank_mask:0xf
	v_mul_f32_e32 v114, v86, v18
	v_mul_f32_e32 v115, v91, v7
	v_add_f32_dpp v101, v109, v109 quad_perm:[1,0,3,2] row_mask:0xf bank_mask:0xf
	v_mul_f32_e32 v116, v86, v115
	v_mul_f32_e32 v103, v92, v1
	v_add_f32_dpp v30, v114, v114 quad_perm:[1,0,3,2] row_mask:0xf bank_mask:0xf
	v_mul_f32_e32 v105, v86, v103
	v_add_f32_dpp v18, v116, v116 quad_perm:[1,0,3,2] row_mask:0xf bank_mask:0xf
	s_nop 0
	v_add_f32_dpp v33, v105, v105 quad_perm:[1,0,3,2] row_mask:0xf bank_mask:0xf
	v_add_f32_dpp v105, v119, v119 quad_perm:[2,3,0,1] row_mask:0xf bank_mask:0xf bound_ctrl:1
	v_add_f32_dpp v18, v18, v18 quad_perm:[2,3,0,1] row_mask:0xf bank_mask:0xf bound_ctrl:1
	v_add_f32_dpp v29, v29, v29 quad_perm:[2,3,0,1] row_mask:0xf bank_mask:0xf bound_ctrl:1
	v_add_f32_dpp v105, v105, v105 row_shr:4 row_mask:0xf bank_mask:0xf bound_ctrl:1
	v_add_f32_dpp v18, v18, v18 row_shr:4 row_mask:0xf bank_mask:0xf bound_ctrl:1
	v_mul_f32_e32 v107, v90, v5
	v_add_f32_dpp v105, v105, v105 row_shr:8 row_mask:0xf bank_mask:0xf bound_ctrl:1
	v_add_f32_dpp v116, v18, v18 row_shr:8 row_mask:0xf bank_mask:0xf bound_ctrl:1
	v_add_f32_dpp v29, v29, v29 row_shr:4 row_mask:0xf bank_mask:0xf bound_ctrl:1
	v_mul_f32_e32 v108, v86, v107
	v_add_f32_dpp v34, v34, v34 quad_perm:[2,3,0,1] row_mask:0xf bank_mask:0xf bound_ctrl:1
	v_add_f32_dpp v29, v29, v29 row_shr:8 row_mask:0xf bank_mask:0xf bound_ctrl:1
	v_add_f32_dpp v105, v105, v105 row_bcast:15 row_mask:0xa bank_mask:0xf
	v_add_f32_dpp v34, v34, v34 row_shr:4 row_mask:0xf bank_mask:0xf bound_ctrl:1
	v_add_f32_dpp v35, v108, v108 quad_perm:[1,0,3,2] row_mask:0xf bank_mask:0xf
	v_add_f32_dpp v102, v102, v102 quad_perm:[2,3,0,1] row_mask:0xf bank_mask:0xf bound_ctrl:1
	v_add_f32_dpp v106, v106, v106 quad_perm:[2,3,0,1] row_mask:0xf bank_mask:0xf bound_ctrl:1
	v_add_f32_dpp v107, v113, v113 quad_perm:[2,3,0,1] row_mask:0xf bank_mask:0xf bound_ctrl:1
	v_add_f32_dpp v34, v34, v34 row_shr:8 row_mask:0xf bank_mask:0xf bound_ctrl:1
	v_add_f32_dpp v113, v29, v29 row_bcast:15 row_mask:0xa bank_mask:0xf
	v_add_f32_dpp v102, v102, v102 row_shr:4 row_mask:0xf bank_mask:0xf bound_ctrl:1
	v_add_f32_dpp v106, v106, v106 row_shr:4 row_mask:0xf bank_mask:0xf bound_ctrl:1
	v_add_f32_dpp v101, v101, v101 quad_perm:[2,3,0,1] row_mask:0xf bank_mask:0xf bound_ctrl:1
	v_add_f32_dpp v102, v102, v102 row_shr:8 row_mask:0xf bank_mask:0xf bound_ctrl:1
	v_add_f32_dpp v108, v106, v106 row_shr:8 row_mask:0xf bank_mask:0xf bound_ctrl:1
	v_add_f32_dpp v106, v34, v34 row_bcast:15 row_mask:0xa bank_mask:0xf
	v_add_f32_dpp v101, v101, v101 row_shr:4 row_mask:0xf bank_mask:0xf bound_ctrl:1
	s_nop 0
	v_add_f32_dpp v2, v2, v2 quad_perm:[2,3,0,1] row_mask:0xf bank_mask:0xf bound_ctrl:1
	v_add_f32_dpp v32, v32, v32 quad_perm:[2,3,0,1] row_mask:0xf bank_mask:0xf bound_ctrl:1
	v_add_f32_dpp v115, v101, v101 row_shr:8 row_mask:0xf bank_mask:0xf bound_ctrl:1
	v_add_f32_dpp v101, v102, v102 row_bcast:15 row_mask:0xa bank_mask:0xf
	v_add_f32_dpp v2, v2, v2 row_shr:4 row_mask:0xf bank_mask:0xf bound_ctrl:1
	v_add_f32_dpp v32, v32, v32 row_shr:4 row_mask:0xf bank_mask:0xf bound_ctrl:1
	s_nop 0
	v_add_f32_dpp v2, v2, v2 row_shr:8 row_mask:0xf bank_mask:0xf bound_ctrl:1
	v_add_f32_dpp v109, v32, v32 row_shr:8 row_mask:0xf bank_mask:0xf bound_ctrl:1
	v_add_f32_dpp v32, v108, v108 row_bcast:15 row_mask:0xa bank_mask:0xf
	v_add_f32_dpp v107, v107, v107 row_shr:4 row_mask:0xf bank_mask:0xf bound_ctrl:1
	s_nop 0
	v_add_f32_dpp v31, v31, v31 quad_perm:[2,3,0,1] row_mask:0xf bank_mask:0xf bound_ctrl:1
	v_add_f32_dpp v107, v107, v107 row_shr:8 row_mask:0xf bank_mask:0xf bound_ctrl:1
	v_add_f32_dpp v29, v2, v2 row_bcast:15 row_mask:0xa bank_mask:0xf
	v_add_f32_dpp v31, v31, v31 row_shr:4 row_mask:0xf bank_mask:0xf bound_ctrl:1
	v_add_f32_dpp v19, v19, v19 quad_perm:[2,3,0,1] row_mask:0xf bank_mask:0xf bound_ctrl:1
	s_nop 0
	v_add_f32_dpp v31, v31, v31 row_shr:8 row_mask:0xf bank_mask:0xf bound_ctrl:1
	v_add_f32_dpp v18, v107, v107 row_bcast:15 row_mask:0xa bank_mask:0xf
	v_add_f32_dpp v19, v19, v19 row_shr:4 row_mask:0xf bank_mask:0xf bound_ctrl:1
	v_mul_f32_e32 v117, v89, v9
	s_nop 0
	v_add_f32_dpp v19, v19, v19 row_shr:8 row_mask:0xf bank_mask:0xf bound_ctrl:1
	v_add_f32_dpp v2, v31, v31 row_bcast:15 row_mask:0xa bank_mask:0xf
	v_mul_f32_e32 v118, v86, v117
	s_nop 0
	v_add_f32_dpp v33, v33, v33 quad_perm:[2,3,0,1] row_mask:0xf bank_mask:0xf bound_ctrl:1
	v_add_f32_dpp v34, v19, v19 row_bcast:15 row_mask:0xa bank_mask:0xf
	s_nop 0
	v_add_f32_dpp v33, v33, v33 row_shr:4 row_mask:0xf bank_mask:0xf bound_ctrl:1
	v_add_f32_dpp v103, v118, v118 quad_perm:[1,0,3,2] row_mask:0xf bank_mask:0xf
	v_add_f32_dpp v35, v35, v35 quad_perm:[2,3,0,1] row_mask:0xf bank_mask:0xf bound_ctrl:1
	v_add_f32_dpp v33, v33, v33 row_shr:8 row_mask:0xf bank_mask:0xf bound_ctrl:1
	v_add_f32_dpp v117, v109, v109 row_bcast:15 row_mask:0xa bank_mask:0xf
	v_add_f32_dpp v35, v35, v35 row_shr:4 row_mask:0xf bank_mask:0xf bound_ctrl:1
	v_add_f32_dpp v30, v30, v30 quad_perm:[2,3,0,1] row_mask:0xf bank_mask:0xf bound_ctrl:1
	s_nop 0
	v_add_f32_dpp v35, v35, v35 row_shr:8 row_mask:0xf bank_mask:0xf bound_ctrl:1
	v_add_f32_dpp v114, v33, v33 row_bcast:15 row_mask:0xa bank_mask:0xf
	v_add_f32_dpp v30, v30, v30 row_shr:4 row_mask:0xf bank_mask:0xf bound_ctrl:1
	s_ashr_i32 s0, s44, 11
	v_add_f32_dpp v107, v35, v35 row_bcast:15 row_mask:0xa bank_mask:0xf
	v_add_f32_dpp v30, v30, v30 row_shr:8 row_mask:0xf bank_mask:0xf bound_ctrl:1
	s_lshl_b32 s4, s44, 6
	v_add_f32_dpp v102, v115, v115 row_bcast:15 row_mask:0xa bank_mask:0xf
	v_add_f32_dpp v103, v103, v103 quad_perm:[2,3,0,1] row_mask:0xf bank_mask:0xf bound_ctrl:1
	s_ashr_i32 s1, s0, 31
	v_add_f32_dpp v33, v30, v30 row_bcast:15 row_mask:0xa bank_mask:0xf
	s_and_b32 s4, s4, 0x1fc0
	v_add_f32_dpp v103, v103, v103 row_shr:4 row_mask:0xf bank_mask:0xf bound_ctrl:1
	s_lshl_b64 s[0:1], s[0:1], 13
	s_nop 0
	v_add_f32_dpp v103, v103, v103 row_shr:8 row_mask:0xf bank_mask:0xf bound_ctrl:1
	v_add_f32_dpp v30, v116, v116 row_bcast:15 row_mask:0xa bank_mask:0xf
	s_add_i32 s4, s4, s33
	s_add_u32 s0, s0, s4
	v_add_f32_dpp v19, v103, v103 row_bcast:15 row_mask:0xa bank_mask:0xf
	s_addc_u32 s1, s1, 0
	s_lshr_b32 s4, s44, 5
	s_and_b32 s4, s4, 60
	v_readlane_b32 s6, v233, 36
	v_mov_b32_e32 v28, v23
	v_add_f32_dpp v123, v105, v105 row_bcast:31 row_mask:0xc bank_mask:0xf
	v_add_f32_dpp v126, v34, v34 row_bcast:31 row_mask:0xc bank_mask:0xf
	v_readlane_b32 s7, v233, 37
	s_add_u32 s22, s6, s4
	v_add_f32_dpp v113, v113, v113 row_bcast:31 row_mask:0xc bank_mask:0xf
	v_add_f32_dpp v106, v106, v106 row_bcast:31 row_mask:0xc bank_mask:0xf
	v_add_f32_dpp v101, v101, v101 row_bcast:31 row_mask:0xc bank_mask:0xf
	v_add_f32_dpp v32, v32, v32 row_bcast:31 row_mask:0xc bank_mask:0xf
	v_add_f32_dpp v29, v29, v29 row_bcast:31 row_mask:0xc bank_mask:0xf
	v_add_f32_dpp v18, v18, v18 row_bcast:31 row_mask:0xc bank_mask:0xf
	v_add_f32_dpp v2, v2, v2 row_bcast:31 row_mask:0xc bank_mask:0xf
	v_add_f32_dpp v117, v117, v117 row_bcast:31 row_mask:0xc bank_mask:0xf
	v_cmp_eq_u32_e32 vcc, 0, v28
	s_addc_u32 s23, s7, 0
	v_readlane_b32 s6, v123, 63
	v_readlane_b32 s7, v126, 63
	s_and_saveexec_b64 s[4:5], vcc
	s_cbranch_execz .LBB0_682
	s_lshl_b64 s[8:9], s[0:1], 6
	s_add_u32 s8, s22, s8
	s_addc_u32 s9, s23, s9
	v_mov_b32_e32 v123, s7
	global_store_dword v3, v123, s[8:9] sc0 sc1
.LBB0_682:
	s_or_b64 exec, exec, s[4:5]
	v_readlane_b32 s7, v113, 63
	v_readlane_b32 s8, v117, 63
	s_and_saveexec_b64 s[4:5], vcc
	s_cbranch_execz .LBB0_684
	s_lshl_b64 s[18:19], s[0:1], 6
	s_add_u32 s18, s22, s18
	s_addc_u32 s19, s23, s19
	v_mov_b32_e32 v113, s8
	global_store_dword v3, v113, s[18:19] offset:64 sc0 sc1
.LBB0_684:
	s_or_b64 exec, exec, s[4:5]
	v_add_f32_dpp v113, v114, v114 row_bcast:31 row_mask:0xc bank_mask:0xf
	v_readlane_b32 s8, v106, 63
	v_readlane_b32 s9, v113, 63
	s_and_saveexec_b64 s[4:5], vcc
	s_cbranch_execz .LBB0_686
	s_lshl_b64 s[18:19], s[0:1], 6
	s_add_u32 s18, s22, s18
	s_addc_u32 s19, s23, s19
	v_mov_b32_e32 v106, s9
	global_store_dword v3, v106, s[18:19] offset:128 sc0 sc1
.LBB0_686:
	s_or_b64 exec, exec, s[4:5]
	v_add_f32_dpp v106, v107, v107 row_bcast:31 row_mask:0xc bank_mask:0xf
	v_readlane_b32 s9, v101, 63
	v_readlane_b32 s17, v106, 63
	s_and_saveexec_b64 s[4:5], vcc
	s_cbranch_execz .LBB0_688
	s_lshl_b64 s[18:19], s[0:1], 6
	s_add_u32 s18, s22, s18
	s_addc_u32 s19, s23, s19
	v_mov_b32_e32 v101, s17
	global_store_dword v3, v101, s[18:19] offset:192 sc0 sc1
.LBB0_688:
	s_or_b64 exec, exec, s[4:5]
	v_add_f32_dpp v101, v102, v102 row_bcast:31 row_mask:0xc bank_mask:0xf
	v_readlane_b32 s17, v32, 63
	v_readlane_b32 s18, v101, 63
	s_and_saveexec_b64 s[4:5], vcc
	s_cbranch_execz .LBB0_690
	s_lshl_b64 s[46:47], s[0:1], 6
	s_add_u32 s46, s22, s46
	s_addc_u32 s47, s23, s47
	v_mov_b32_e32 v32, s18
	global_store_dword v3, v32, s[46:47] offset:256 sc0 sc1
.LBB0_690:
	s_or_b64 exec, exec, s[4:5]
	v_add_f32_dpp v32, v33, v33 row_bcast:31 row_mask:0xc bank_mask:0xf
	v_readlane_b32 s18, v29, 63
	v_readlane_b32 s19, v32, 63
	s_and_saveexec_b64 s[4:5], vcc
	s_cbranch_execz .LBB0_692
	s_lshl_b64 s[46:47], s[0:1], 6
	s_add_u32 s46, s22, s46
	s_addc_u32 s47, s23, s47
	v_mov_b32_e32 v29, s19
	global_store_dword v3, v29, s[46:47] offset:320 sc0 sc1
.LBB0_692:
	s_or_b64 exec, exec, s[4:5]
	v_add_f32_dpp v29, v30, v30 row_bcast:31 row_mask:0xc bank_mask:0xf
	v_readlane_b32 s19, v18, 63
	v_readlane_b32 s45, v29, 63
	s_and_saveexec_b64 s[4:5], vcc
	s_cbranch_execz .LBB0_694
	s_lshl_b64 s[46:47], s[0:1], 6
	s_add_u32 s46, s22, s46
	s_addc_u32 s47, s23, s47
	v_mov_b32_e32 v18, s45
	global_store_dword v3, v18, s[46:47] offset:384 sc0 sc1
.LBB0_694:
	s_or_b64 exec, exec, s[4:5]
	v_add_f32_dpp v18, v19, v19 row_bcast:31 row_mask:0xc bank_mask:0xf
	v_readlane_b32 s46, v2, 63
	v_readlane_b32 s45, v18, 63
	s_and_saveexec_b64 s[4:5], vcc
	s_cbranch_execz .LBB0_696
	s_lshl_b64 s[0:1], s[0:1], 6
	s_add_u32 s0, s22, s0
	s_addc_u32 s1, s23, s1
	v_mov_b32_e32 v2, s45
	global_store_dword v3, v2, s[0:1] offset:448 sc0 sc1
